# deserialized load chains: gmlp staging+epilogue loads hoisted, scan2 carry loop batched, final-norm partial loads widened, ffn epilogue drain removed
# speedup vs baseline: 1.0044x; 1.0044x over previous
; __device__ __forceinline__ void scan2_phase(const unsigned* AB, const float* Ls, const float* Hs, const bf16_t* G, bf16_t* Y, int gtid, int NT) {
;     for (int idx = gtid; idx < 8 * 64 * 256; idx += NT) {
;         const int cq = idx & 255, j = (idx >> 8) & 63, b = idx >> 14, c = 4 * cq; const size_t row0 = (size_t)b * SEQ + j * 64;
;         f32x4 h = (f32x4){0.f, 0.f, 0.f, 0.f};
; #pragma unroll 8
;         for (int jj = 0; jj < j; ++jj) { const size_t o = ((size_t)b * 64 + jj) * 1024 + c; const f32x4 l = *(const f32x4*)(Ls + o), hh = *(const f32x4*)(Hs + o);
; #pragma unroll
;             for (int k = 0; k < 4; ++k) h[k] = __expf(l[k]) * h[k] + hh[k]; }
.LBB0_64:
	s_mov_b32 s98, 0xffdf9000
	s_mov_b32 s99, -1
	s_add_i32 s0, s0, 8
	s_mov_b64 s[22:23], 0x8000
	v_lshl_add_u64 v[14:15], v[8:9], 0, s[98:99]
	s_mov_b32 s98, 0xffff9000
	v_lshl_add_u64 v[16:17], v[8:9], 0, s[98:99]
	global_load_dwordx4 v[22:25], v[14:15], off
	v_lshl_add_u64 v[14:15], v[14:15], 0, s[28:29]
	global_load_dwordx4 v[26:29], v[16:17], off
	v_lshl_add_u64 v[16:17], v[16:17], 0, s[28:29]
	global_load_dwordx4 v[30:33], v[14:15], off
	v_lshl_add_u64 v[14:15], v[14:15], 0, s[28:29]
	global_load_dwordx4 v[34:37], v[16:17], off
	v_lshl_add_u64 v[16:17], v[16:17], 0, s[28:29]
	global_load_dwordx4 v[38:41], v[14:15], off
	v_lshl_add_u64 v[14:15], v[14:15], 0, s[28:29]
	global_load_dwordx4 v[42:45], v[16:17], off
	v_lshl_add_u64 v[16:17], v[16:17], 0, s[28:29]
	global_load_dwordx4 v[46:49], v[14:15], off
	v_lshl_add_u64 v[14:15], v[14:15], 0, s[28:29]
	global_load_dwordx4 v[50:53], v[16:17], off
	v_lshl_add_u64 v[16:17], v[16:17], 0, s[28:29]
	global_load_dwordx4 v[54:57], v[14:15], off
	v_lshl_add_u64 v[14:15], v[14:15], 0, s[28:29]
	global_load_dwordx4 v[58:61], v[16:17], off
	v_lshl_add_u64 v[16:17], v[16:17], 0, s[28:29]
	global_load_dwordx4 v[62:65], v[14:15], off
	v_lshl_add_u64 v[14:15], v[14:15], 0, s[28:29]
	global_load_dwordx4 v[66:69], v[16:17], off
	v_lshl_add_u64 v[16:17], v[16:17], 0, s[28:29]
	global_load_dwordx4 v[70:73], v[14:15], off
	v_lshl_add_u64 v[14:15], v[14:15], 0, s[28:29]
	global_load_dwordx4 v[74:77], v[16:17], off
	v_lshl_add_u64 v[16:17], v[16:17], 0, s[28:29]
	global_load_dwordx4 v[78:81], v[14:15], off
	global_load_dwordx4 v[82:85], v[16:17], off
	v_cmp_eq_u32_e32 vcc, s0, v13
	v_lshl_add_u64 v[8:9], v[8:9], 0, s[22:23]
	s_or_b64 s[20:21], vcc, s[20:21]
	s_waitcnt vmcnt(14)
	v_mul_f32_e32 v24, 0x3fb8aa3b, v24
	v_mul_f32_e32 v25, 0x3fb8aa3b, v25
	v_exp_f32_e32 v24, v24
	v_exp_f32_e32 v25, v25
	v_mul_f32_e32 v22, 0x3fb8aa3b, v22
	v_mul_f32_e32 v23, 0x3fb8aa3b, v23
	v_exp_f32_e32 v22, v22
	v_exp_f32_e32 v23, v23
	v_pk_fma_f32 v[4:5], v[4:5], v[24:25], v[28:29]
	s_nop 0
	v_pk_fma_f32 v[6:7], v[6:7], v[22:23], v[26:27]
	s_waitcnt vmcnt(12)
	v_mul_f32_e32 v32, 0x3fb8aa3b, v32
	v_mul_f32_e32 v33, 0x3fb8aa3b, v33
	v_exp_f32_e32 v32, v32
	v_exp_f32_e32 v33, v33
	v_mul_f32_e32 v30, 0x3fb8aa3b, v30
	v_mul_f32_e32 v31, 0x3fb8aa3b, v31
	v_exp_f32_e32 v30, v30
	v_exp_f32_e32 v31, v31
	v_pk_fma_f32 v[4:5], v[4:5], v[32:33], v[36:37]
	s_nop 0
	v_pk_fma_f32 v[6:7], v[6:7], v[30:31], v[34:35]
	s_waitcnt vmcnt(10)
	v_mul_f32_e32 v40, 0x3fb8aa3b, v40
	v_mul_f32_e32 v41, 0x3fb8aa3b, v41
	v_exp_f32_e32 v40, v40
	v_exp_f32_e32 v41, v41
	v_mul_f32_e32 v38, 0x3fb8aa3b, v38
	v_mul_f32_e32 v39, 0x3fb8aa3b, v39
	v_exp_f32_e32 v38, v38
	v_exp_f32_e32 v39, v39
	v_pk_fma_f32 v[4:5], v[4:5], v[40:41], v[44:45]
	s_nop 0
	v_pk_fma_f32 v[6:7], v[6:7], v[38:39], v[42:43]
	s_waitcnt vmcnt(8)
	v_mul_f32_e32 v48, 0x3fb8aa3b, v48
	v_mul_f32_e32 v49, 0x3fb8aa3b, v49
	v_exp_f32_e32 v48, v48
	v_exp_f32_e32 v49, v49
	v_mul_f32_e32 v46, 0x3fb8aa3b, v46
	v_mul_f32_e32 v47, 0x3fb8aa3b, v47
	v_exp_f32_e32 v46, v46
	v_exp_f32_e32 v47, v47
	v_pk_fma_f32 v[4:5], v[4:5], v[48:49], v[52:53]
	s_nop 0
	v_pk_fma_f32 v[6:7], v[6:7], v[46:47], v[50:51]
	s_waitcnt vmcnt(6)
	v_mul_f32_e32 v56, 0x3fb8aa3b, v56
	v_mul_f32_e32 v57, 0x3fb8aa3b, v57
	v_exp_f32_e32 v56, v56
	v_exp_f32_e32 v57, v57
	v_mul_f32_e32 v54, 0x3fb8aa3b, v54
	v_mul_f32_e32 v55, 0x3fb8aa3b, v55
	v_exp_f32_e32 v54, v54
	v_exp_f32_e32 v55, v55
	v_pk_fma_f32 v[4:5], v[4:5], v[56:57], v[60:61]
	s_nop 0
	v_pk_fma_f32 v[6:7], v[6:7], v[54:55], v[58:59]
	s_waitcnt vmcnt(4)
	v_mul_f32_e32 v64, 0x3fb8aa3b, v64
	v_mul_f32_e32 v65, 0x3fb8aa3b, v65
	v_exp_f32_e32 v64, v64
	v_exp_f32_e32 v65, v65
	v_mul_f32_e32 v62, 0x3fb8aa3b, v62
	v_mul_f32_e32 v63, 0x3fb8aa3b, v63
	v_exp_f32_e32 v62, v62
	v_exp_f32_e32 v63, v63
	v_pk_fma_f32 v[4:5], v[4:5], v[64:65], v[68:69]
	s_nop 0
	v_pk_fma_f32 v[6:7], v[6:7], v[62:63], v[66:67]
	s_waitcnt vmcnt(2)
	v_mul_f32_e32 v72, 0x3fb8aa3b, v72
	v_mul_f32_e32 v73, 0x3fb8aa3b, v73
	v_exp_f32_e32 v72, v72
	v_exp_f32_e32 v73, v73
	v_mul_f32_e32 v70, 0x3fb8aa3b, v70
	v_mul_f32_e32 v71, 0x3fb8aa3b, v71
	v_exp_f32_e32 v70, v70
	v_exp_f32_e32 v71, v71
	v_pk_fma_f32 v[4:5], v[4:5], v[72:73], v[76:77]
	s_nop 0
	v_pk_fma_f32 v[6:7], v[6:7], v[70:71], v[74:75]
	s_waitcnt vmcnt(0)
	v_mul_f32_e32 v80, 0x3fb8aa3b, v80
	v_mul_f32_e32 v81, 0x3fb8aa3b, v81
	v_exp_f32_e32 v80, v80
	v_exp_f32_e32 v81, v81
	v_mul_f32_e32 v78, 0x3fb8aa3b, v78
	v_mul_f32_e32 v79, 0x3fb8aa3b, v79
	v_exp_f32_e32 v78, v78
	v_exp_f32_e32 v79, v79
	v_pk_fma_f32 v[4:5], v[4:5], v[80:81], v[84:85]
	s_nop 0
	v_pk_fma_f32 v[6:7], v[6:7], v[78:79], v[82:83]
	s_andn2_b64 exec, exec, s[20:21]
	s_cbranch_execnz .LBB0_64
	s_or_b64 exec, exec, s[20:21]
	v_readlane_b32 s22, v254, 30
	v_readlane_b32 s23, v254, 31

; #define LAS __attribute__((address_space(3)))
; __device__ __forceinline__ void gmlp_gate_phase(const Params& p, LAS unsigned char* lds, bf16_t* U, const bf16_t* V, const float* ssv, const int tid, const int bx) {
;     ...
;         for (int i = 0; i < 8; ++i) { const int pc = tid + 512 * i, s = pc >> 5, d0 = (pc & 31) * 8;
;             const u32x4 v = *(const u32x4*)(V + (size_t)(tok0 + s) * 2048 + colb + d0);
;             LAS unsigned* dst = (LAS unsigned*)(Vs + s * 258 + d0); dst[0] = v.x; dst[1] = v.y; dst[2] = v.z; dst[3] = v.w; }
;         __syncthreads();
;         f32x4 acc[8][2]; u32x2 upre[8][2];
; #pragma unroll
;         for (int mb = 0; mb < 8; ++mb) { acc[mb][0] = (f32x4){0.f, 0.f, 0.f, 0.f}; acc[mb][1] = (f32x4){0.f, 0.f, 0.f, 0.f};
; #pragma unroll
;             for (int nb = 0; nb < 2; ++nb) upre[mb][nb] = *(const u32x2*)(U + (size_t)(tok0 + mb * 16 + fr) * 2048 + colb + wave * 32 + nb * 16 + 4 * fq); }
; #pragma unroll
;         for (int kk = 0; kk < 4; ++kk) {
;             bf16x8 vf[2];
; #pragma unroll
;             for (int nb = 0; nb < 2; ++nb) { const int d = wave * 32 + nb * 16 + fr;
; #pragma unroll
;                 for (int j = 0; j < 8; ++j) vf[nb][j] = (short)Vs[(kk * 32 + fq * 8 + j) * 258 + d]; }
; #pragma unroll
;             for (int mb = 0; mb < 8; ++mb) { if (32 * kk <= 16 * mb + 15) {
;                 const bf16x8 wf = *(const LAS bf16x8*)(Wm + (mb * 16 + fr) * 136 + kk * 32 + fq * 8);
;                 acc[mb][0] = __builtin_amdgcn_mfma_f32_16x16x32_bf16(vf[0], wf, acc[mb][0], 0, 0, 0);
;                 acc[mb][1] = __builtin_amdgcn_mfma_f32_16x16x32_bf16(vf[1], wf, acc[mb][1], 0, 0, 0); } }
.LBB0_78:
	s_or_b64 exec, exec, s[0:1]
	s_lshl_b32 s0, s72, 9
	s_and_b32 s1, s3, 0x100
	s_or_b32 s0, s0, s1
	v_cvt_pk_bf16_f32 v7, v7, v8
	v_cvt_pk_bf16_f32 v8, v10, v2
	v_cvt_pk_bf16_f32 v6, v11, v6
	v_cvt_pk_bf16_f32 v9, v3, v4
	s_lshl_b32 s72, s0, 1
	s_mov_b32 s73, s93
	ds_write_b128 v168, v[6:9]
	v_lshl_add_u64 v[6:7], v[74:75], 0, s[72:73]
	v_add_u32_e32 v8, 0x8800, v169
	s_waitcnt vmcnt(0)
	ds_write2_b32 v8, v86, v87 offset1:1
	v_add_u32_e32 v2, 0x8808, v169
	ds_write2_b32 v2, v88, v89 offset1:1
	v_add_u32_e32 v8, 0x8800, v170
	ds_write2_b32 v8, v90, v91 offset1:1
	v_add_u32_e32 v2, 0x8808, v170
	ds_write2_b32 v2, v92, v93 offset1:1
	v_add_u32_e32 v8, 0x8800, v171
	ds_write2_b32 v8, v94, v95 offset1:1
	v_add_u32_e32 v2, 0x8808, v171
	ds_write2_b32 v2, v96, v97 offset1:1
	v_add_u32_e32 v8, 0x8800, v172
	ds_write2_b32 v8, v98, v99 offset1:1
	v_add_u32_e32 v2, 0x8808, v172
	ds_write2_b32 v2, v100, v101 offset1:1
	v_add_u32_e32 v8, 0x8800, v173
	ds_write2_b32 v8, v102, v103 offset1:1
	v_add_u32_e32 v2, 0x8808, v173
	ds_write2_b32 v2, v104, v105 offset1:1
	v_add_u32_e32 v8, 0x8800, v174
	ds_write2_b32 v8, v106, v107 offset1:1
	v_add_u32_e32 v2, 0x8808, v174
	ds_write2_b32 v2, v108, v109 offset1:1
	v_add_u32_e32 v8, 0x8800, v175
	ds_write2_b32 v8, v110, v111 offset1:1
	v_add_u32_e32 v2, 0x8808, v175
	ds_write2_b32 v2, v112, v113 offset1:1
	v_add_u32_e32 v6, 0x8800, v176
	ds_write2_b32 v6, v114, v115 offset1:1
	v_add_u32_e32 v2, 0x8808, v176
	ds_write2_b32 v2, v116, v117 offset1:1
	v_or_b32_e32 v4, s85, v138
	v_ashrrev_i32_e32 v5, 31, v4
	v_lshl_add_u64 v[2:3], v[76:77], 0, s[72:73]
	v_lshlrev_b64 v[66:67], 12, v[4:5]
	v_lshl_add_u64 v[4:5], v[2:3], 0, v[66:67]
	s_waitcnt lgkmcnt(0)
	s_barrier
	global_load_dwordx2 v[134:135], v[4:5], off
	global_load_dwordx2 v[130:131], v[4:5], off offset:32
	v_or_b32_e32 v4, s85, v158
	v_ashrrev_i32_e32 v5, 31, v4
	v_lshlrev_b64 v[128:129], 12, v[4:5]
	v_lshl_add_u64 v[4:5], v[2:3], 0, v[128:129]
	global_load_dwordx2 v[126:127], v[4:5], off
	global_load_dwordx2 v[124:125], v[4:5], off offset:32
	v_or_b32_e32 v4, s85, v159
	v_ashrrev_i32_e32 v5, 31, v4
	v_lshlrev_b64 v[122:123], 12, v[4:5]
	v_lshl_add_u64 v[4:5], v[2:3], 0, v[122:123]
	global_load_dwordx2 v[120:121], v[4:5], off
	global_load_dwordx2 v[118:119], v[4:5], off offset:32
	v_or_b32_e32 v4, s85, v160
	v_ashrrev_i32_e32 v5, 31, v4
	v_lshlrev_b64 v[116:117], 12, v[4:5]
	v_lshl_add_u64 v[4:5], v[2:3], 0, v[116:117]
	global_load_dwordx2 v[114:115], v[4:5], off
	global_load_dwordx2 v[112:113], v[4:5], off offset:32
	v_or_b32_e32 v4, s85, v161
	v_ashrrev_i32_e32 v5, 31, v4
	v_lshlrev_b64 v[110:111], 12, v[4:5]
	v_lshl_add_u64 v[4:5], v[2:3], 0, v[110:111]
	global_load_dwordx2 v[108:109], v[4:5], off
	global_load_dwordx2 v[106:107], v[4:5], off offset:32
	v_or_b32_e32 v4, s85, v162
	v_ashrrev_i32_e32 v5, 31, v4
	v_lshlrev_b64 v[104:105], 12, v[4:5]
	v_lshl_add_u64 v[4:5], v[2:3], 0, v[104:105]
	global_load_dwordx2 v[102:103], v[4:5], off
	global_load_dwordx2 v[100:101], v[4:5], off offset:32
	v_or_b32_e32 v4, s85, v163
	v_ashrrev_i32_e32 v5, 31, v4
	v_lshlrev_b64 v[98:99], 12, v[4:5]
	v_lshl_add_u64 v[4:5], v[2:3], 0, v[98:99]
	global_load_dwordx2 v[96:97], v[4:5], off
	global_load_dwordx2 v[92:93], v[4:5], off offset:32
	v_or_b32_e32 v4, s78, v164
	v_ashrrev_i32_e32 v5, 31, v4
	v_lshlrev_b64 v[90:91], 12, v[4:5]
	v_lshl_add_u64 v[2:3], v[2:3], 0, v[90:91]
	global_load_dwordx2 v[88:89], v[2:3], off
	global_load_dwordx2 v[86:87], v[2:3], off offset:32
	ds_read_u16 v2, v177 offset:35332
	ds_read_u16 v3, v177 offset:35848
	ds_read_u16 v6, v177 offset:36364
	ds_read_u16 v4, v177 offset:36880
	ds_read_u16 v7, v177 offset:37396
	ds_read_u16 v5, v177 offset:37912
	ds_read_u16 v8, v177 offset:38428
	ds_read_u16 v9, v177 offset:34816
	ds_read_u16 v10, v177 offset:34848
	ds_read_u16 v11, v177 offset:35364
	ds_read_u16 v12, v177 offset:35880
	ds_read_u16 v13, v177 offset:36396
	ds_read_u16 v14, v177 offset:36912
	ds_read_u16 v15, v177 offset:37428
	ds_read_u16 v16, v177 offset:37944
	ds_read_u16 v17, v177 offset:38460
	s_waitcnt lgkmcnt(0)
	v_perm_b32 v5, v8, v5, s33
	v_perm_b32 v4, v7, v4, s33
	v_perm_b32 v3, v6, v3, s33
	v_perm_b32 v2, v2, v9, s33
	v_perm_b32 v9, v17, v16, s33
	v_perm_b32 v8, v15, v14, s33
	v_perm_b32 v7, v13, v12, s33
	v_perm_b32 v6, v11, v10, s33
	ds_read_b128 v[10:13], v178
	ds_read_b128 v[18:21], v178 offset:13056
	s_waitcnt lgkmcnt(0)
	v_mfma_f32_16x16x32_bf16 v[62:65], v[2:5], v[10:13], 0
	ds_read_b128 v[26:29], v178 offset:17408
	ds_read_b128 v[34:37], v178 offset:21760
	v_readlane_b32 s72, v253, 53
	v_mfma_f32_16x16x32_bf16 v[58:61], v[6:9], v[10:13], 0
	ds_read_b128 v[10:13], v178 offset:4352
	v_readlane_b32 s73, v253, 54
	v_readlane_b32 s74, v253, 55
	s_waitcnt lgkmcnt(0)
	v_mfma_f32_16x16x32_bf16 v[54:57], v[2:5], v[10:13], 0
	v_readlane_b32 s75, v253, 56
	v_mfma_f32_16x16x32_bf16 v[50:53], v[6:9], v[10:13], 0
	ds_read_b128 v[10:13], v178 offset:8704
	v_mfma_f32_16x16x32_bf16 v[204:207], v[2:5], v[34:37], 0
	v_mfma_f32_16x16x32_bf16 v[208:211], v[6:9], v[34:37], 0
	ds_read_b128 v[34:37], v178 offset:26112
	s_waitcnt lgkmcnt(0)
	v_mfma_f32_16x16x32_bf16 v[212:215], v[2:5], v[34:37], 0
	v_mfma_f32_16x16x32_bf16 v[216:219], v[6:9], v[34:37], 0
	ds_read_b128 v[34:37], v178 offset:30464
	v_mfma_f32_16x16x32_bf16 v[14:17], v[2:5], v[10:13], 0
	v_mfma_f32_16x16x32_bf16 v[10:13], v[6:9], v[10:13], 0
	v_mfma_f32_16x16x32_bf16 v[22:25], v[2:5], v[18:21], 0
	v_mfma_f32_16x16x32_bf16 v[18:21], v[6:9], v[18:21], 0
	v_mfma_f32_16x16x32_bf16 v[30:33], v[2:5], v[26:29], 0
	v_mfma_f32_16x16x32_bf16 v[26:29], v[6:9], v[26:29], 0
	s_waitcnt lgkmcnt(0)
; #define LAS __attribute__((address_space(3)))
; __device__ __forceinline__ unsigned cvt_pk_bf16(float lo, float hi) { unsigned r; asm("v_cvt_pk_bf16_f32 %0, %1, %2" : "=v"(r) : "v"(lo), "v"(hi)); return r; }
; __device__ __forceinline__ float bf_lo(unsigned w) { return __uint_as_float(w << 16); }
; __device__ __forceinline__ float bf_hi(unsigned w) { return __uint_as_float(w & 0xffff0000u); }
; __device__ __forceinline__ void gmlp_gate_phase(const Params& p, LAS unsigned char* lds, bf16_t* U, const bf16_t* V, const float* ssv, const int tid, const int bx) {
;     ...
;         for (int kk = 0; kk < 4; ++kk) {
;             bf16x8 vf[2];
; #pragma unroll
;             for (int nb = 0; nb < 2; ++nb) { const int d = wave * 32 + nb * 16 + fr;
; #pragma unroll
;                 for (int j = 0; j < 8; ++j) vf[nb][j] = (short)Vs[(kk * 32 + fq * 8 + j) * 258 + d]; }
; #pragma unroll
;             for (int mb = 0; mb < 8; ++mb) { if (32 * kk <= 16 * mb + 15) {
;                 const bf16x8 wf = *(const LAS bf16x8*)(Wm + (mb * 16 + fr) * 136 + kk * 32 + fq * 8);
;                 acc[mb][0] = __builtin_amdgcn_mfma_f32_16x16x32_bf16(vf[0], wf, acc[mb][0], 0, 0, 0);
;                 acc[mb][1] = __builtin_amdgcn_mfma_f32_16x16x32_bf16(vf[1], wf, acc[mb][1], 0, 0, 0); } }
;         }
; #pragma unroll
;         for (int mb = 0; mb < 8; ++mb) { const int t = mb * 16 + fr; const float bs = b_s[g * 128 + t];
; #pragma unroll
;             for (int nb = 0; nb < 2; ++nb) { const int col = colb + wave * 32 + nb * 16 + 4 * fq;
;                 const f32x4 gg = *(const f32x4*)(gv + col); bf16_t* up = U + (size_t)(tok0 + t) * 2048 + col;
;                 const u32x2 uw = upre[mb][nb];
;                 const float o0 = bf_lo(uw.x) * (acc[mb][nb][0] * gg[0] + bs), o1 = bf_hi(uw.x) * (acc[mb][nb][1] * gg[1] + bs), o2 = bf_lo(uw.y) * (acc[mb][nb][2] * gg[2] + bs), o3 = bf_hi(uw.y) * (acc[mb][nb][3] * gg[3] + bs);
;                 u32x2 ow; ow.x = cvt_pk_bf16(o0, o1); ow.y = cvt_pk_bf16(o2, o3); *(u32x2*)up = ow; } }
	v_mfma_f32_16x16x32_bf16 v[2:5], v[2:5], v[34:37], 0
	v_mfma_f32_16x16x32_bf16 v[6:9], v[6:9], v[34:37], 0
	ds_read_u16 v34, v177 offset:51328
	ds_read_u16 v35, v177 offset:51844
	ds_read_u16 v36, v177 offset:52360
	ds_read_u16 v37, v177 offset:52876
	ds_read_u16 v38, v177 offset:53392
	ds_read_u16 v39, v177 offset:53908
	ds_read_u16 v40, v177 offset:54424
	ds_read_u16 v41, v177 offset:54940
	ds_read_u16 v42, v177 offset:51360
	ds_read_u16 v43, v177 offset:51876
	ds_read_u16 v44, v177 offset:52392
	ds_read_u16 v45, v177 offset:52908
	ds_read_u16 v46, v177 offset:53424
	ds_read_u16 v47, v177 offset:53940
	ds_read_u16 v48, v177 offset:54456
	ds_read_u16 v49, v177 offset:54972
	s_waitcnt lgkmcnt(0)
	v_perm_b32 v221, v37, v36, s33
	v_perm_b32 v220, v35, v34, s33
	v_perm_b32 v226, v47, v46, s33
	v_perm_b32 v225, v45, v44, s33
	v_perm_b32 v227, v49, v48, s33
	v_perm_b32 v224, v43, v42, s33
	ds_read_b128 v[34:37], v178 offset:8768
	v_perm_b32 v223, v41, v40, s33
	v_perm_b32 v222, v39, v38, s33
	s_waitcnt lgkmcnt(0)
	v_mfma_f32_16x16x32_bf16 v[42:45], v[224:227], v[34:37], v[10:13]
	s_nop 2
	ds_read_b128 v[10:13], v178 offset:13120
	v_mfma_f32_16x16x32_bf16 v[46:49], v[220:223], v[34:37], v[14:17]
	s_waitcnt lgkmcnt(0)
	v_mfma_f32_16x16x32_bf16 v[38:41], v[220:223], v[10:13], v[22:25]
	v_mfma_f32_16x16x32_bf16 v[34:37], v[224:227], v[10:13], v[18:21]
	ds_read_b128 v[10:13], v178 offset:17472
	s_nop 1
	ds_read_b128 v[18:21], v178 offset:21824
	s_waitcnt lgkmcnt(0)
	v_mfma_f32_16x16x32_bf16 v[14:17], v[220:223], v[10:13], v[30:33]
	v_mfma_f32_16x16x32_bf16 v[10:13], v[224:227], v[10:13], v[26:29]
	s_nop 2
	ds_read_b128 v[26:29], v178 offset:26176
	v_mfma_f32_16x16x32_bf16 v[22:25], v[220:223], v[18:21], v[204:207]
	v_mfma_f32_16x16x32_bf16 v[18:21], v[224:227], v[18:21], v[208:211]
	s_waitcnt lgkmcnt(0)
	v_mfma_f32_16x16x32_bf16 v[204:207], v[220:223], v[26:29], v[212:215]
	v_mfma_f32_16x16x32_bf16 v[208:211], v[224:227], v[26:29], v[216:219]
	ds_read_b128 v[26:29], v178 offset:30528
	s_waitcnt lgkmcnt(0)
	v_mfma_f32_16x16x32_bf16 v[2:5], v[220:223], v[26:29], v[2:5]
	v_mfma_f32_16x16x32_bf16 v[6:9], v[224:227], v[26:29], v[6:9]
	ds_read_u16 v26, v179 offset:34816
	ds_read_u16 v27, v179 offset:34848
	ds_read_u16 v28, v180 offset:34816
	ds_read_u16 v29, v180 offset:34848
	ds_read_u16 v30, v181 offset:34816
	ds_read_u16 v31, v181 offset:34848
	ds_read_u16 v32, v182 offset:34816
	ds_read_u16 v33, v182 offset:34848
	ds_read_u16 v68, v183 offset:34816
	ds_read_u16 v69, v183 offset:34848
	ds_read_u16 v94, v184 offset:34816
	ds_read_u16 v95, v184 offset:34848
	ds_read_u16 v132, v185 offset:34816
	ds_read_u16 v133, v185 offset:34848
	ds_read_u16 v136, v186 offset:34816
	ds_read_u16 v137, v186 offset:34848
	s_waitcnt lgkmcnt(0)
	v_perm_b32 v214, v94, v68, s33
	v_perm_b32 v213, v32, v30, s33
	v_perm_b32 v212, v28, v26, s33
	v_perm_b32 v215, v136, v132, s33
	v_perm_b32 v219, v137, v133, s33
	v_perm_b32 v218, v95, v69, s33
	v_perm_b32 v217, v33, v31, s33
	v_perm_b32 v216, v29, v27, s33
	ds_read_b128 v[26:29], v178 offset:17536
	s_waitcnt lgkmcnt(0)
	v_mfma_f32_16x16x32_bf16 v[30:33], v[212:215], v[26:29], v[14:17]
	v_mfma_f32_16x16x32_bf16 v[26:29], v[216:219], v[26:29], v[10:13]
	s_nop 2
	ds_read_b128 v[10:13], v178 offset:21888
	s_waitcnt lgkmcnt(0)
	v_mfma_f32_16x16x32_bf16 v[22:25], v[212:215], v[10:13], v[22:25]
	v_mfma_f32_16x16x32_bf16 v[18:21], v[216:219], v[10:13], v[18:21]
	ds_read_b128 v[10:13], v178 offset:26240
	s_waitcnt lgkmcnt(0)
	v_mfma_f32_16x16x32_bf16 v[14:17], v[212:215], v[10:13], v[204:207]
	s_nop 2
	ds_read_b128 v[204:207], v178 offset:30592
	s_waitcnt lgkmcnt(0)
	v_mfma_f32_16x16x32_bf16 v[2:5], v[212:215], v[204:207], v[2:5]
	v_mfma_f32_16x16x32_bf16 v[204:207], v[216:219], v[204:207], v[6:9]
	s_nop 2
	ds_read_u16 v6, v187 offset:34816
	ds_read_u16 v68, v187 offset:34848
	ds_read_u16 v69, v188 offset:34816
	ds_read_u16 v94, v188 offset:34848
	ds_read_u16 v7, v189 offset:34816
	ds_read_u16 v95, v189 offset:34848
	ds_read_u16 v132, v190 offset:34816
	ds_read_u16 v133, v190 offset:34848
	ds_read_u16 v8, v191 offset:34816
	ds_read_u16 v136, v191 offset:34848
	ds_read_u16 v137, v192 offset:34816
	ds_read_u16 v194, v192 offset:34848
	ds_read_u16 v9, v193 offset:34816
	ds_read_u16 v195, v193 offset:34848
	ds_read_u16 v196, v202 offset:34816
	ds_read_u16 v197, v202 offset:34848
	s_waitcnt lgkmcnt(0)
	v_perm_b32 v7, v132, v7, s33
	v_add_u32_e32 v132, s0, v143
	v_mfma_f32_16x16x32_bf16 v[10:13], v[216:219], v[10:13], v[208:211]
	v_readlane_b32 s0, v253, 47
	v_readlane_b32 s1, v253, 48
	v_perm_b32 v8, v137, v8, s33
	v_perm_b32 v209, v133, v95, s33
	v_perm_b32 v208, v94, v68, s33
	v_ashrrev_i32_e32 v133, 31, v132
	v_or_b32_e32 v68, s92, v138
	v_lshl_add_u64 v[94:95], v[132:133], 2, s[72:73]
	v_lshlrev_b32_e32 v68, 2, v68
	v_perm_b32 v6, v69, v6, s33
	v_perm_b32 v210, v194, v136, s33
	v_lshl_add_u64 v[136:137], s[70:71], 0, v[66:67]
	v_perm_b32 v9, v196, v9, s33
	v_perm_b32 v211, v197, v195, s33
	ds_read_b128 v[212:215], v178 offset:26304
	v_lshlrev_b64 v[132:133], 1, v[132:133]
	s_waitcnt vmcnt(0)
	v_lshlrev_b32_e32 v195, 16, v134
	v_lshl_add_u64 v[136:137], v[136:137], 0, v[132:133]
	s_waitcnt lgkmcnt(0)
	v_mfma_f32_16x16x32_bf16 v[14:17], v[6:9], v[212:215], v[14:17]
	v_fma_f32 v62, v62, v228, v236
	v_and_b32_e32 v66, 0xffff0000, v134
	v_fma_f32 v63, v63, v229, v236
	v_mul_f32_e32 v63, v63, v66
	v_lshlrev_b32_e32 v66, 16, v135
	v_fma_f32 v64, v64, v230, v236
	v_mul_f32_e32 v62, v62, v195
	v_mul_f32_e32 v64, v64, v66
	v_and_b32_e32 v66, 0xffff0000, v135
	v_fma_f32 v65, v65, v231, v236
	v_mfma_f32_16x16x32_bf16 v[10:13], v[208:211], v[212:215], v[10:13]
	ds_read_b128 v[212:215], v203 offset:192
	v_mul_f32_e32 v65, v65, v66
	v_cvt_pk_bf16_f32 v62, v62, v63
	v_cvt_pk_bf16_f32 v63, v64, v65
	global_store_dwordx2 v[136:137], v[62:63], off
	v_lshlrev_b32_e32 v66, 16, v130
	s_waitcnt lgkmcnt(0)
; __device__ __forceinline__ unsigned cvt_pk_bf16(float lo, float hi) { unsigned r; asm("v_cvt_pk_bf16_f32 %0, %1, %2" : "=v"(r) : "v"(lo), "v"(hi)); return r; }
; __device__ __forceinline__ float bf_lo(unsigned w) { return __uint_as_float(w << 16); }
; __device__ __forceinline__ float bf_hi(unsigned w) { return __uint_as_float(w & 0xffff0000u); }
; __device__ __forceinline__ void gmlp_gate_phase(const Params& p, LAS unsigned char* lds, bf16_t* U, const bf16_t* V, const float* ssv, const int tid, const int bx) {
;     ...
;         for (int mb = 0; mb < 8; ++mb) { const int t = mb * 16 + fr; const float bs = b_s[g * 128 + t];
; #pragma unroll
;             for (int nb = 0; nb < 2; ++nb) { const int col = colb + wave * 32 + nb * 16 + 4 * fq;
;                 const f32x4 gg = *(const f32x4*)(gv + col); bf16_t* up = U + (size_t)(tok0 + t) * 2048 + col;
;                 const u32x2 uw = upre[mb][nb];
;                 const float o0 = bf_lo(uw.x) * (acc[mb][nb][0] * gg[0] + bs), o1 = bf_hi(uw.x) * (acc[mb][nb][1] * gg[1] + bs), o2 = bf_lo(uw.y) * (acc[mb][nb][2] * gg[2] + bs), o3 = bf_hi(uw.y) * (acc[mb][nb][3] * gg[3] + bs);
;                 u32x2 ow; ow.x = cvt_pk_bf16(o0, o1); ow.y = cvt_pk_bf16(o2, o3); *(u32x2*)up = ow; } }
	v_mfma_f32_16x16x32_bf16 v[6:9], v[6:9], v[212:215], v[2:5]
	v_fma_f32 v58, v58, v232, v236
	v_and_b32_e32 v62, 0xffff0000, v130
	v_fma_f32 v59, v59, v233, v236
	v_mul_f32_e32 v58, v58, v66
	v_mul_f32_e32 v59, v59, v62
	v_lshlrev_b32_e32 v62, 16, v131
	v_fma_f32 v60, v60, v234, v236
	v_mul_f32_e32 v60, v60, v62
	v_and_b32_e32 v62, 0xffff0000, v131
	v_fmac_f32_e32 v236, v61, v235
	v_cvt_pk_bf16_f32 v58, v58, v59
	v_mul_f32_e32 v61, v236, v62
	v_cvt_pk_bf16_f32 v59, v60, v61
	global_store_dwordx2 v[136:137], v[58:59], off offset:32
	v_add_lshl_u32 v58, s92, v138, 2
	v_lshl_add_u64 v[64:65], s[70:71], 0, v[128:129]
	v_lshlrev_b32_e32 v66, 16, v126
	v_lshl_add_u64 v[64:65], v[64:65], 0, v[132:133]
	v_mfma_f32_16x16x32_bf16 v[2:5], v[208:211], v[212:215], v[204:207]
	v_fma_f32 v54, v54, v228, v237
	v_and_b32_e32 v60, 0xffff0000, v126
	v_fma_f32 v55, v55, v229, v237
	v_mul_f32_e32 v55, v55, v60
	v_lshlrev_b32_e32 v60, 16, v127
	v_fma_f32 v56, v56, v230, v237
	v_mul_f32_e32 v54, v54, v66
	v_mul_f32_e32 v56, v56, v60
	v_and_b32_e32 v60, 0xffff0000, v127
	v_fma_f32 v57, v57, v231, v237
	v_mul_f32_e32 v57, v57, v60
	v_cvt_pk_bf16_f32 v54, v54, v55
	v_cvt_pk_bf16_f32 v55, v56, v57
	global_store_dwordx2 v[64:65], v[54:55], off
	v_lshlrev_b32_e32 v60, 16, v124
	v_fma_f32 v50, v50, v232, v237
	v_and_b32_e32 v54, 0xffff0000, v124
	v_fma_f32 v51, v51, v233, v237
	v_mul_f32_e32 v51, v51, v54
	v_lshlrev_b32_e32 v54, 16, v125
	v_fma_f32 v52, v52, v234, v237
	v_mul_f32_e32 v50, v50, v60
	v_mul_f32_e32 v52, v52, v54
	v_and_b32_e32 v54, 0xffff0000, v125
	v_fmac_f32_e32 v237, v53, v235
	v_mul_f32_e32 v53, v237, v54
	v_cvt_pk_bf16_f32 v50, v50, v51
	v_cvt_pk_bf16_f32 v51, v52, v53
	global_store_dwordx2 v[64:65], v[50:51], off offset:32
	v_lshl_add_u64 v[54:55], s[70:71], 0, v[122:123]
	v_lshlrev_b32_e32 v57, 16, v120
	v_lshl_add_u64 v[54:55], v[54:55], 0, v[132:133]
	v_fma_f32 v46, v46, v228, v238
	v_and_b32_e32 v50, 0xffff0000, v120
	v_fma_f32 v47, v47, v229, v238
	v_mul_f32_e32 v47, v47, v50
	v_lshlrev_b32_e32 v50, 16, v121
	v_fma_f32 v48, v48, v230, v238
	v_mul_f32_e32 v46, v46, v57
	v_mul_f32_e32 v48, v48, v50
	v_and_b32_e32 v50, 0xffff0000, v121
	v_fma_f32 v49, v49, v231, v238
	v_mul_f32_e32 v49, v49, v50
	v_cvt_pk_bf16_f32 v46, v46, v47
	v_cvt_pk_bf16_f32 v47, v48, v49
	global_store_dwordx2 v[54:55], v[46:47], off
	v_lshlrev_b32_e32 v50, 16, v118
	v_fma_f32 v42, v42, v232, v238
	v_and_b32_e32 v46, 0xffff0000, v118
	v_fma_f32 v43, v43, v233, v238
	v_mul_f32_e32 v43, v43, v46
	v_lshlrev_b32_e32 v46, 16, v119
	v_fma_f32 v44, v44, v234, v238
	v_mul_f32_e32 v42, v42, v50
	v_mul_f32_e32 v44, v44, v46
	v_and_b32_e32 v46, 0xffff0000, v119
	v_fmac_f32_e32 v238, v45, v235
	v_mul_f32_e32 v45, v238, v46
	v_cvt_pk_bf16_f32 v42, v42, v43
	v_cvt_pk_bf16_f32 v43, v44, v45
	global_store_dwordx2 v[54:55], v[42:43], off offset:32
	v_lshl_add_u64 v[46:47], s[70:71], 0, v[116:117]
	v_lshlrev_b32_e32 v49, 16, v114
	v_lshl_add_u64 v[46:47], v[46:47], 0, v[132:133]
	v_fma_f32 v38, v38, v228, v239
	v_and_b32_e32 v42, 0xffff0000, v114
	v_fma_f32 v39, v39, v229, v239
	v_mul_f32_e32 v39, v39, v42
	v_lshlrev_b32_e32 v42, 16, v115
	v_fma_f32 v40, v40, v230, v239
	v_mul_f32_e32 v38, v38, v49
	v_mul_f32_e32 v40, v40, v42
	v_and_b32_e32 v42, 0xffff0000, v115
	v_fma_f32 v41, v41, v231, v239
	v_mul_f32_e32 v41, v41, v42
	v_cvt_pk_bf16_f32 v38, v38, v39
	v_cvt_pk_bf16_f32 v39, v40, v41
	global_store_dwordx2 v[46:47], v[38:39], off
	v_lshlrev_b32_e32 v42, 16, v112
	v_fma_f32 v34, v34, v232, v239
	v_and_b32_e32 v38, 0xffff0000, v112
	v_fma_f32 v35, v35, v233, v239
	v_mul_f32_e32 v35, v35, v38
	v_lshlrev_b32_e32 v38, 16, v113
	v_fma_f32 v36, v36, v234, v239
	v_mul_f32_e32 v34, v34, v42
	v_mul_f32_e32 v36, v36, v38
	v_and_b32_e32 v38, 0xffff0000, v113
	v_fmac_f32_e32 v239, v37, v235
	v_mul_f32_e32 v37, v239, v38
	v_cvt_pk_bf16_f32 v34, v34, v35
	v_cvt_pk_bf16_f32 v35, v36, v37
	global_store_dwordx2 v[46:47], v[34:35], off offset:32
	v_lshl_add_u64 v[38:39], s[70:71], 0, v[110:111]
	v_lshlrev_b32_e32 v41, 16, v108
	v_lshl_add_u64 v[38:39], v[38:39], 0, v[132:133]
	v_fma_f32 v30, v30, v228, v198
	v_and_b32_e32 v34, 0xffff0000, v108
	v_fma_f32 v31, v31, v229, v198
	v_mul_f32_e32 v31, v31, v34
	v_lshlrev_b32_e32 v34, 16, v109
	v_fma_f32 v32, v32, v230, v198
	v_mul_f32_e32 v30, v30, v41
	v_mul_f32_e32 v32, v32, v34
	v_and_b32_e32 v34, 0xffff0000, v109
	v_fma_f32 v33, v33, v231, v198
	v_mul_f32_e32 v33, v33, v34
	v_cvt_pk_bf16_f32 v30, v30, v31
	v_cvt_pk_bf16_f32 v31, v32, v33
	global_store_dwordx2 v[38:39], v[30:31], off
	v_lshlrev_b32_e32 v34, 16, v106
	v_fma_f32 v26, v26, v232, v198
	v_and_b32_e32 v30, 0xffff0000, v106
	v_fma_f32 v27, v27, v233, v198
	v_mul_f32_e32 v27, v27, v30
	v_lshlrev_b32_e32 v30, 16, v107
	v_fma_f32 v28, v28, v234, v198
	v_mul_f32_e32 v26, v26, v34
	v_mul_f32_e32 v28, v28, v30
	v_and_b32_e32 v30, 0xffff0000, v107
	v_fmac_f32_e32 v198, v29, v235
	v_mul_f32_e32 v29, v198, v30
	v_cvt_pk_bf16_f32 v26, v26, v27
	v_cvt_pk_bf16_f32 v27, v28, v29
	global_store_dwordx2 v[38:39], v[26:27], off offset:32
	v_lshl_add_u64 v[30:31], s[70:71], 0, v[104:105]
	v_lshlrev_b32_e32 v33, 16, v102
	v_lshl_add_u64 v[30:31], v[30:31], 0, v[132:133]
	v_fma_f32 v22, v22, v228, v199
	v_and_b32_e32 v26, 0xffff0000, v102
	v_fma_f32 v23, v23, v229, v199
	v_mul_f32_e32 v23, v23, v26
	v_lshlrev_b32_e32 v26, 16, v103
	v_fma_f32 v24, v24, v230, v199
	v_mul_f32_e32 v22, v22, v33
	v_mul_f32_e32 v24, v24, v26
	v_and_b32_e32 v26, 0xffff0000, v103
	v_fma_f32 v25, v25, v231, v199
	v_mul_f32_e32 v25, v25, v26
	v_cvt_pk_bf16_f32 v22, v22, v23
	v_cvt_pk_bf16_f32 v23, v24, v25
	global_store_dwordx2 v[30:31], v[22:23], off
; __device__ __forceinline__ void gmlp_gate_phase(const Params& p, LAS unsigned char* lds, bf16_t* U, const bf16_t* V, const float* ssv, const int tid, const int bx) {
;     ...
;     for (int item = bx; item < 2048; item += gridDim.x) {
;         const int chunk = item >> 3, g = (item >> 1) & 3, half = item & 1;
;         const int tok0 = chunk * 128, colb = g * 512 + half * 256;
;         {
;             const float* pp = ssv + (size_t)(tok0 + (tid >> 2)) * 32 + (tid & 3) * 8; const f32x4 a = *(const f32x4*)pp, b = *(const f32x4*)(pp + 4);
;             float q = ((a[0] + a[1]) + (a[2] + a[3])) + ((b[0] + b[1]) + (b[2] + b[3])); q += __shfl_xor(q, 1); q += __shfl_xor(q, 2);
;             if ((tid & 3) == 0) Rv[tid >> 2] = rsqrtf(q * (1.0f / 2048.0f) + EPS); }
;         __syncthreads();
; #pragma unroll
;         for (int i = 0; i < 4; ++i) { const int pc = tid + 512 * i, t = pc >> 4, s0 = (pc & 15) * 8;
;             const f32x4 w0 = *(const f32x4*)(w_s + ((size_t)g * 128 + t) * 128 + s0), w1 = *(const f32x4*)(w_s + ((size_t)g * 128 + t) * 128 + s0 + 4);
;             float f[8];
; #pragma unroll
;             for (int j = 0; j < 4; ++j) { f[j] = (s0 + j <= t) ? w0[j] * Rv[s0 + j] : 0.f; f[4 + j] = (s0 + 4 + j <= t) ? w1[j] * Rv[s0 + 4 + j] : 0.f; }
;             *(LAS u32x4*)(Wm + t * 136 + s0) = pack8(f); }
; #pragma unroll
;         for (int i = 0; i < 8; ++i) { const int pc = tid + 512 * i, s = pc >> 5, d0 = (pc & 31) * 8;
;             const u32x4 v = *(const u32x4*)(V + (size_t)(tok0 + s) * 2048 + colb + d0);
;             LAS unsigned* dst = (LAS unsigned*)(Vs + s * 258 + d0); dst[0] = v.x; dst[1] = v.y; dst[2] = v.z; dst[3] = v.w; }
;     ...
;         for (int mb = 0; mb < 8; ++mb) { const int t = mb * 16 + fr; const float bs = b_s[g * 128 + t];
; #pragma unroll
;             for (int nb = 0; nb < 2; ++nb) { const int col = colb + wave * 32 + nb * 16 + 4 * fq;
;                 const f32x4 gg = *(const f32x4*)(gv + col); bf16_t* up = U + (size_t)(tok0 + t) * 2048 + col;
;                 const u32x2 uw = upre[mb][nb];
;                 const float o0 = bf_lo(uw.x) * (acc[mb][nb][0] * gg[0] + bs), o1 = bf_hi(uw.x) * (acc[mb][nb][1] * gg[1] + bs), o2 = bf_lo(uw.y) * (acc[mb][nb][2] * gg[2] + bs), o3 = bf_hi(uw.y) * (acc[mb][nb][3] * gg[3] + bs);
;                 u32x2 ow; ow.x = cvt_pk_bf16(o0, o1); ow.y = cvt_pk_bf16(o2, o3); *(u32x2*)up = ow; } }
	v_lshlrev_b32_e32 v26, 16, v100
	v_fma_f32 v18, v18, v232, v199
	v_and_b32_e32 v22, 0xffff0000, v100
	v_fma_f32 v19, v19, v233, v199
	v_mul_f32_e32 v19, v19, v22
	v_lshlrev_b32_e32 v22, 16, v101
	v_fma_f32 v20, v20, v234, v199
	v_mul_f32_e32 v18, v18, v26
	v_mul_f32_e32 v20, v20, v22
	v_and_b32_e32 v22, 0xffff0000, v101
	v_fmac_f32_e32 v199, v21, v235
	v_mul_f32_e32 v21, v199, v22
	v_cvt_pk_bf16_f32 v18, v18, v19
	v_cvt_pk_bf16_f32 v19, v20, v21
	global_store_dwordx2 v[30:31], v[18:19], off offset:32
	v_lshl_add_u64 v[22:23], s[70:71], 0, v[98:99]
	v_lshlrev_b32_e32 v25, 16, v96
	v_lshl_add_u64 v[22:23], v[22:23], 0, v[132:133]
	v_fma_f32 v14, v14, v228, v151
	v_and_b32_e32 v18, 0xffff0000, v96
	v_fma_f32 v15, v15, v229, v151
	v_mul_f32_e32 v15, v15, v18
	v_lshlrev_b32_e32 v18, 16, v97
	v_fma_f32 v16, v16, v230, v151
	v_mul_f32_e32 v14, v14, v25
	v_mul_f32_e32 v16, v16, v18
	v_and_b32_e32 v18, 0xffff0000, v97
	v_fma_f32 v17, v17, v231, v151
	v_mul_f32_e32 v17, v17, v18
	v_cvt_pk_bf16_f32 v14, v14, v15
	v_cvt_pk_bf16_f32 v15, v16, v17
	global_store_dwordx2 v[22:23], v[14:15], off
	v_lshlrev_b32_e32 v18, 16, v92
	v_fma_f32 v10, v10, v232, v151
	v_and_b32_e32 v14, 0xffff0000, v92
	v_fma_f32 v11, v11, v233, v151
	v_mul_f32_e32 v11, v11, v14
	v_lshlrev_b32_e32 v14, 16, v93
	v_fma_f32 v12, v12, v234, v151
	v_mul_f32_e32 v10, v10, v18
	v_mul_f32_e32 v12, v12, v14
	v_and_b32_e32 v14, 0xffff0000, v93
	v_fmac_f32_e32 v151, v13, v235
	v_mul_f32_e32 v13, v151, v14
	v_cvt_pk_bf16_f32 v10, v10, v11
	v_cvt_pk_bf16_f32 v11, v12, v13
	global_store_dwordx2 v[22:23], v[10:11], off offset:32
	v_lshl_add_u64 v[14:15], s[70:71], 0, v[90:91]
	v_lshlrev_b32_e32 v17, 16, v88
	v_lshl_add_u64 v[14:15], v[14:15], 0, v[132:133]
	v_readlane_b32 s0, v254, 8
	s_add_i32 s79, s79, s0
	v_readlane_b32 s0, v253, 39
	s_add_i32 s3, s3, s0
	v_readlane_b32 s0, v253, 40
	s_add_i32 s78, s78, s0
	s_cmpk_gt_i32 s79, 0x7ff
	v_readlane_b32 s1, v254, 9
	v_fma_f32 v6, v6, v228, v152
	v_and_b32_e32 v10, 0xffff0000, v88
	v_fma_f32 v7, v7, v229, v152
	v_mul_f32_e32 v7, v7, v10
	v_lshlrev_b32_e32 v10, 16, v89
	v_fma_f32 v8, v8, v230, v152
	v_mul_f32_e32 v6, v6, v17
	v_mul_f32_e32 v8, v8, v10
	v_and_b32_e32 v10, 0xffff0000, v89
	v_fma_f32 v9, v9, v231, v152
	v_mul_f32_e32 v9, v9, v10
	v_cvt_pk_bf16_f32 v6, v6, v7
	v_cvt_pk_bf16_f32 v7, v8, v9
	global_store_dwordx2 v[14:15], v[6:7], off
	v_lshlrev_b32_e32 v10, 16, v86
	v_fma_f32 v2, v2, v232, v152
	v_and_b32_e32 v6, 0xffff0000, v86
	v_fma_f32 v3, v3, v233, v152
	v_mul_f32_e32 v3, v3, v6
	v_lshlrev_b32_e32 v6, 16, v87
	v_fma_f32 v4, v4, v234, v152
	v_mul_f32_e32 v2, v2, v10
	v_mul_f32_e32 v4, v4, v6
	v_and_b32_e32 v6, 0xffff0000, v87
	v_fmac_f32_e32 v152, v5, v235
	v_mul_f32_e32 v5, v152, v6
	v_cvt_pk_bf16_f32 v2, v2, v3
	v_cvt_pk_bf16_f32 v3, v4, v5
	global_store_dwordx2 v[14:15], v[2:3], off offset:32
	s_waitcnt lgkmcnt(0)
	s_barrier
	s_cbranch_scc1 .LBB0_145
.LBB0_79:
	s_and_b32 s85, s78, 0xffffff80
	v_add_u32_e32 v2, s85, v139
	v_ashrrev_i32_e32 v3, 31, v2
	v_lshlrev_b64 v[2:3], 7, v[2:3]
	v_lshl_add_u64 v[6:7], v[70:71], 0, v[2:3]
	global_load_dwordx4 v[2:5], v[6:7], off
	s_nop 0
	global_load_dwordx4 v[6:9], v[6:7], off offset:16
	s_bfe_u32 s98, s79, 0x20001
	s_lshl_b32 s98, s98, 9
	s_and_b32 s99, s3, 0x100
	s_or_b32 s98, s98, s99
	v_add_u32_e32 v118, s98, v143
	s_lshl_b32 s98, s98, 1
	s_mov_b32 s99, 0
	v_lshl_add_u64 v[120:121], v[74:75], 0, s[98:99]
	s_add_i32 s98, s85, 0
	v_add_u32_e32 v122, s98, v150
	v_ashrrev_i32_e32 v123, 31, v122
	v_lshlrev_b64 v[122:123], 12, v[122:123]
	v_lshl_add_u64 v[122:123], v[120:121], 0, v[122:123]
	global_load_dwordx4 v[86:89], v[122:123], off
	s_add_i32 s98, s85, 16
	v_add_u32_e32 v122, s98, v150
	v_ashrrev_i32_e32 v123, 31, v122
	v_lshlrev_b64 v[122:123], 12, v[122:123]
	v_lshl_add_u64 v[122:123], v[120:121], 0, v[122:123]
	global_load_dwordx4 v[90:93], v[122:123], off
	s_add_i32 s98, s85, 32
	v_add_u32_e32 v122, s98, v150
	v_ashrrev_i32_e32 v123, 31, v122
	v_lshlrev_b64 v[122:123], 12, v[122:123]
	v_lshl_add_u64 v[122:123], v[120:121], 0, v[122:123]
	global_load_dwordx4 v[94:97], v[122:123], off
	s_add_i32 s98, s85, 48
	v_add_u32_e32 v122, s98, v150
	v_ashrrev_i32_e32 v123, 31, v122
	v_lshlrev_b64 v[122:123], 12, v[122:123]
	v_lshl_add_u64 v[122:123], v[120:121], 0, v[122:123]
	global_load_dwordx4 v[98:101], v[122:123], off
	s_add_i32 s98, s85, 64
	v_add_u32_e32 v122, s98, v150
	v_ashrrev_i32_e32 v123, 31, v122
	v_lshlrev_b64 v[122:123], 12, v[122:123]
	v_lshl_add_u64 v[122:123], v[120:121], 0, v[122:123]
	global_load_dwordx4 v[102:105], v[122:123], off
	s_add_i32 s98, s85, 80
	v_add_u32_e32 v122, s98, v150
	v_ashrrev_i32_e32 v123, 31, v122
	v_lshlrev_b64 v[122:123], 12, v[122:123]
	v_lshl_add_u64 v[122:123], v[120:121], 0, v[122:123]
	global_load_dwordx4 v[106:109], v[122:123], off
	s_add_i32 s98, s85, 96
	v_add_u32_e32 v122, s98, v150
	v_ashrrev_i32_e32 v123, 31, v122
	v_lshlrev_b64 v[122:123], 12, v[122:123]
	v_lshl_add_u64 v[122:123], v[120:121], 0, v[122:123]
	global_load_dwordx4 v[110:113], v[122:123], off
	s_add_i32 s98, s85, 112
	v_add_u32_e32 v122, s98, v150
	v_ashrrev_i32_e32 v123, 31, v122
	v_lshlrev_b64 v[122:123], 12, v[122:123]
	v_lshl_add_u64 v[122:123], v[120:121], 0, v[122:123]
	global_load_dwordx4 v[114:117], v[122:123], off
	s_bfe_u32 s98, s79, 0x20001
	s_lshl_b32 s98, s98, 7
	v_add_lshl_u32 v119, s98, v138, 2
	v_readlane_b32 s98, v253, 53
	v_readlane_b32 s99, v253, 54
	v_lshlrev_b32_e32 v118, 2, v118
	s_nop 4
	global_load_dwordx4 v[228:231], v118, s[98:99]
	global_load_dwordx4 v[232:235], v118, s[98:99] offset:64
	v_readlane_b32 s98, v253, 47
	v_readlane_b32 s99, v253, 48
	s_nop 4
	global_load_dword v236, v119, s[98:99]
	global_load_dword v237, v119, s[98:99] offset:64
	global_load_dword v238, v119, s[98:99] offset:128
	global_load_dword v239, v119, s[98:99] offset:192
	global_load_dword v198, v119, s[98:99] offset:256
	global_load_dword v199, v119, s[98:99] offset:320
	global_load_dword v151, v119, s[98:99] offset:384
	global_load_dword v152, v119, s[98:99] offset:448
	s_waitcnt vmcnt(18) lgkmcnt(0)
	v_add_f32_e32 v2, v2, v3
	v_add_f32_e32 v3, v4, v5
	v_add_f32_e32 v4, v6, v7
	v_add_f32_e32 v5, v8, v9
	v_add_f32_e32 v2, v2, v3
	v_add_f32_e32 v3, v4, v5
	v_add_f32_e32 v2, v2, v3
	ds_bpermute_b32 v3, v140, v2
	s_waitcnt lgkmcnt(0)
	v_add_f32_e32 v2, v2, v3
	ds_bpermute_b32 v3, v141, v2
	s_and_saveexec_b64 s[0:1], vcc
	s_cbranch_execz .LBB0_81
	s_waitcnt lgkmcnt(0)
	v_add_f32_e32 v2, v2, v3
	v_fmamk_f32 v2, v2, 0x3a000000, v240
	v_mul_f32_e32 v3, 0x4b800000, v2
	v_cmp_gt_f32_e64 s[72:73], s83, v2
	s_nop 1
	v_cndmask_b32_e64 v2, v2, v3, s[72:73]
	v_rsq_f32_e32 v2, v2
	s_nop 0
	v_mul_f32_e32 v3, 0x45800000, v2
	v_cndmask_b32_e64 v2, v2, v3, s[72:73]
	ds_write_b32 v142, v2

;     __device__ __forceinline__ void operator()(f32x4 (&acc)[2][2][4][2], const Unit& u, int wr, int wc, int fr, int fq) const {
;     ...
;         if (wv < 4) { const int r = wv * 64 + fq * 16 + fr; const float* pp = ssn + (size_t)(u.pm * BM + r) * 16; float q = 0.f;
; #pragma unroll
;             for (int k = 0; k < 16; ++k) q += __hip_atomic_load(pp + k, __ATOMIC_RELAXED, __HIP_MEMORY_SCOPE_AGENT);
;             R[r] = rsqrtf(q * (1.0f / 1024.0f) + EPS); }
.LBB0_375:
	s_barrier
	s_andn2_b64 vcc, exec, s[28:29]
	s_cbranch_vccnz .LBB0_377
	v_and_b32_e32 v2, -16, v195
	v_add_u32_e32 v2, s58, v2
	v_or_b32_e32 v4, v2, v194
	v_add_u32_e32 v2, s38, v4
	s_waitcnt lgkmcnt(0)
	v_ashrrev_i32_e32 v3, 31, v2
	v_lshlrev_b64 v[2:3], 6, v[2:3]
	v_lshl_add_u64 v[2:3], s[22:23], 0, v[2:3]
	global_load_dwordx4 v[150:153], v[2:3], off sc1
	global_load_dwordx4 v[154:157], v[2:3], off offset:16 sc1
	global_load_dwordx4 v[158:161], v[2:3], off offset:32 sc1
	global_load_dwordx4 v[162:165], v[2:3], off offset:48 sc1
	s_waitcnt vmcnt(0) lgkmcnt(0)
	v_add_f32_e32 v5, 0, v150
	v_add_f32_e32 v5, v5, v151
	v_add_f32_e32 v5, v5, v152
	v_add_f32_e32 v5, v5, v153
	v_add_f32_e32 v5, v5, v154
	v_add_f32_e32 v5, v5, v155
	v_add_f32_e32 v5, v5, v156
	v_add_f32_e32 v5, v5, v157
	v_add_f32_e32 v5, v5, v158
	v_add_f32_e32 v5, v5, v159
	v_add_f32_e32 v5, v5, v160
	v_add_f32_e32 v5, v5, v161
	v_add_f32_e32 v5, v5, v162
	v_add_f32_e32 v5, v5, v163
	v_add_f32_e32 v5, v5, v164
	v_add_f32_e32 v2, v5, v165
	v_fmamk_f32 v2, v2, 0x3a800000, v240
	v_cmp_gt_f32_e32 vcc, s73, v2
	v_mul_f32_e32 v3, 0x4b800000, v2
	s_nop 0
	v_cndmask_b32_e32 v2, v2, v3, vcc
	v_rsq_f32_e32 v2, v2
	s_nop 0
	v_mul_f32_e32 v3, 0x45800000, v2
	v_cndmask_b32_e32 v2, v2, v3, vcc
	v_lshl_add_u32 v3, v4, 2, 0
	v_add_u32_e32 v3, 0x21c00, v3
	ds_write_b32 v3, v2

; #define LAS __attribute__((address_space(3)))
;     __device__ __forceinline__ void operator()(f32x4 (&acc)[2][2][4][2], const Unit& u, int wr, int wc, int fr, int fq, int next_pn) const {
;     ...
;         asm volatile("s_waitcnt lgkmcnt(0)" ::: "memory"); __builtin_amdgcn_s_barrier(); asm volatile("" ::: "memory"); __builtin_amdgcn_sched_barrier(0);
;         int rowb = u.pm * BM + rl0; asm volatile("" : "+v"(rowb));
; #pragma unroll
;         for (int ai = 0; ai < 2; ++ai) { const int sl = 2 * ai + wr;
;             u32x2 keep[4];
; #pragma unroll
;             for (int hf = 0; hf < 2; ++hf) {
;                 __builtin_amdgcn_sched_barrier(0);
;                 const LAS float* wl = WL + tcol + 4 * hf;
;                 const f32x4 wg0 = *(const LAS f32x4*)(wl), wg1 = *(const LAS f32x4*)(wl + 256), wg2 = *(const LAS f32x4*)(wl + 512), bg = *(const LAS f32x4*)(wl + 768);
;                 const f32x4 wv0 = *(const LAS f32x4*)(wl + 128), wv1 = *(const LAS f32x4*)(wl + 384), wv2 = *(const LAS f32x4*)(wl + 640), bvv = *(const LAS f32x4*)(wl + 896);
;                 f32x4 hg62 = (f32x4){0.f, 0.f, 0.f, 0.f}, hg63 = hg62, hv62 = hg62, hv63 = hg62;
;                 if (sl > 0) { const LAS float* hp = H + ((sl - 1) * 2) * 256 + tcol + 4 * hf; hg62 = *(const LAS f32x4*)hp; hv62 = *(const LAS f32x4*)(hp + 128); hg63 = *(const LAS f32x4*)(hp + 256); hv63 = *(const LAS f32x4*)(hp + 384); }
.LBB0_737:
	s_waitcnt lgkmcnt(0)
	s_barrier
	v_lshl_add_u32 v194, s89, 8, v140
	v_lshl_add_u32 v195, v0, 2, s8
	ds_read_b128 v[140:143], v195
	ds_read_b128 v[144:147], v195 offset:512
	ds_read_b128 v[152:155], v195 offset:1024
	ds_read_b128 v[148:151], v195 offset:1536
	ds_read_b128 v[164:167], v195 offset:2048
	ds_read_b128 v[156:159], v195 offset:2560
	ds_read_b128 v[168:171], v195 offset:3072
	ds_read_b128 v[160:163], v195 offset:3584
	v_mov_b32_e32 v130, 0
	v_cmp_ne_u32_e64 s[8:9], 1, v132
	s_andn2_b64 vcc, exec, s[34:35]
	v_mov_b32_e32 v136, 0
	v_mov_b32_e32 v137, 0
	v_mov_b32_e32 v138, 0
	v_mov_b32_e32 v139, 0
	v_mov_b32_e32 v132, 0
	v_mov_b32_e32 v133, 0
	v_mov_b32_e32 v134, 0
	v_mov_b32_e32 v135, 0
	v_mov_b32_e32 v172, 0
	v_mov_b32_e32 v173, 0
	v_mov_b32_e32 v174, 0
	v_mov_b32_e32 v175, 0
	v_mov_b32_e32 v176, 0
	v_mov_b32_e32 v177, 0
	v_mov_b32_e32 v178, 0
	v_mov_b32_e32 v179, 0
	s_cbranch_vccnz .LBB0_739
	v_lshl_add_u32 v131, v0, 2, s79
	ds_read_b128 v[176:179], v131
	ds_read_b128 v[132:135], v131 offset:512
	ds_read_b128 v[172:175], v131 offset:1024
	ds_read_b128 v[136:139], v131 offset:1536

;     __device__ __forceinline__ void operator()(f32x4 (&acc)[2][2][4][2], const Unit& u, int wr, int wc, int fr, int fq, int next_pn) const {
;     ...
;                 for (int j = 0; j < 4; ++j) { sg3[j] = dpp_shr1(hg63[j], acc[ai][0][3][hf][j]); sg2[j] = dpp_shr1(hg62[j], acc[ai][0][2][hf][j]); sv3[j] = dpp_shr1(hv63[j], acc[ai][1][3][hf][j]); sv2[j] = dpp_shr1(hv62[j], acc[ai][1][2][hf][j]); }
; #pragma unroll
;                 for (int m = 0; m < 4; ++m) {
;                     const f32x4 cg = acc[ai][0][m][hf], cv = acc[ai][1][m][hf];
;                     const f32x4 g1v = (m == 0) ? sg3 : acc[ai][0][m == 0 ? 0 : m - 1][hf], g2v = (m == 0) ? sg2 : (m == 1) ? sg3 : acc[ai][0][m < 2 ? 0 : m - 2][hf];
;                     const f32x4 v1v = (m == 0) ? sv3 : acc[ai][1][m == 0 ? 0 : m - 1][hf], v2v = (m == 0) ? sv2 : (m == 1) ? sv3 : acc[ai][1][m < 2 ? 0 : m - 2][hf];
;                     float o[4];
; #pragma unroll
;                     for (int j2 = 0; j2 < 2; ++j2) {
;                         const int j = 2 * j2;
;                         const f32x2v g1 = {g1v[j], g1v[j + 1]}, g2 = {g2v[j], g2v[j + 1]}, v1 = {v1v[j], v1v[j + 1]}, v2 = {v2v[j], v2v[j + 1]};
;                         const f32x2v c_g = {cg[j], cg[j + 1]}, c_v = {cv[j], cv[j + 1]};
;                         const f32x2v gc = (f32x2v){wg0[j], wg0[j + 1]} * g2 + ((f32x2v){wg1[j], wg1[j + 1]} * g1 + ((f32x2v){wg2[j], wg2[j + 1]} * c_g + (f32x2v){bg[j], bg[j + 1]}));
;                         const f32x2v vc = (f32x2v){wv0[j], wv0[j + 1]} * v2 + ((f32x2v){wv1[j], wv1[j + 1]} * v1 + ((f32x2v){wv2[j], wv2[j + 1]} * c_v + (f32x2v){bvv[j], bvv[j + 1]}));
;                         const f32x2v e = gc * (-1.4426950408889634f); f32x2v t; t.x = __builtin_amdgcn_exp2f(e.x); t.y = __builtin_amdgcn_exp2f(e.y);
;                         const f32x2v d = t + 1.0f; f32x2v r; r.x = __builtin_amdgcn_rcpf(d.x); r.y = __builtin_amdgcn_rcpf(d.y);
;                         const f32x2v oo = (gc * r) * vc; o[j] = oo.x; o[j + 1] = oo.y; }
;                     u32x2 w; w.x = cvt_pk_bf16(o[0], o[1]); w.y = cvt_pk_bf16(o[2], o[3]);
;                     if (hf == 0) keep[m] = w;
;                     else *(u32x4*)(A2 + (size_t)(rowb + ai * HALF + m) * FFW + c0) = (u32x4){keep[m].x, keep[m].y, w.x, w.y}; }
.LBB0_745:
	s_waitcnt lgkmcnt(0)
	v_mov_b32_dpp v86, v10 row_shr:1 row_mask:0xf bank_mask:0xf
	v_mov_b32_dpp v87, v11 row_shr:1 row_mask:0xf bank_mask:0xf
	v_pk_fma_f32 v[44:45], v[30:31], v[78:79], v[82:83]
	v_mov_b32_dpp v94, v2 row_shr:1 row_mask:0xf bank_mask:0xf
	v_mov_b32_dpp v58, v14 row_shr:1 row_mask:0xf bank_mask:0xf
	v_mov_b32_dpp v95, v3 row_shr:1 row_mask:0xf bank_mask:0xf
	v_mov_b32_dpp v59, v15 row_shr:1 row_mask:0xf bank_mask:0xf
	v_pk_fma_f32 v[44:45], v[74:75], v[86:87], v[44:45]
	v_pk_fma_f32 v[68:69], v[34:35], v[54:55], v[70:71]
	v_mov_b32_dpp v90, v6 row_shr:1 row_mask:0xf bank_mask:0xf
	v_mov_b32_dpp v91, v7 row_shr:1 row_mask:0xf bank_mask:0xf
	v_pk_fma_f32 v[44:45], v[46:47], v[94:95], v[44:45]
	v_pk_fma_f32 v[68:69], v[50:51], v[58:59], v[68:69]
	v_mov_b32_dpp v88, v12 row_shr:1 row_mask:0xf bank_mask:0xf
	v_pk_fma_f32 v[68:69], v[38:39], v[90:91], v[68:69]
	v_pk_mul_f32 v[90:91], v[44:45], s[88:89] op_sel_hi:[1,0]
	v_mov_b32_dpp v89, v13 row_shr:1 row_mask:0xf bank_mask:0xf
	v_exp_f32_e32 v90, v90
	v_exp_f32_e32 v91, v91
	v_pk_fma_f32 v[28:29], v[32:33], v[80:81], v[84:85]
	v_mov_b32_dpp v96, v4 row_shr:1 row_mask:0xf bank_mask:0xf
	v_mov_b32_dpp v97, v5 row_shr:1 row_mask:0xf bank_mask:0xf
	v_pk_add_f32 v[90:91], v[90:91], 1.0 op_sel_hi:[1,0]
	v_pk_fma_f32 v[28:29], v[76:77], v[88:89], v[28:29]
	v_rcp_f32_e32 v90, v90
	v_rcp_f32_e32 v91, v91
	v_pk_fma_f32 v[28:29], v[48:49], v[96:97], v[28:29]
	v_mov_b32_dpp v60, v16 row_shr:1 row_mask:0xf bank_mask:0xf
	v_mov_b32_dpp v61, v17 row_shr:1 row_mask:0xf bank_mask:0xf
	v_pk_mul_f32 v[44:45], v[44:45], v[90:91]
	v_pk_fma_f32 v[64:65], v[36:37], v[56:57], v[72:73]
	v_pk_mul_f32 v[44:45], v[68:69], v[44:45]
	v_pk_mul_f32 v[68:69], v[28:29], s[88:89] op_sel_hi:[1,0]
	v_mov_b32_dpp v92, v8 row_shr:1 row_mask:0xf bank_mask:0xf
	v_exp_f32_e32 v68, v68
	v_exp_f32_e32 v69, v69
	v_mov_b32_dpp v93, v9 row_shr:1 row_mask:0xf bank_mask:0xf
	v_pk_fma_f32 v[64:65], v[52:53], v[60:61], v[64:65]
	v_add_u32_e32 v0, 0x80, v194
	v_pk_add_f32 v[68:69], v[68:69], 1.0 op_sel_hi:[1,0]
	v_pk_fma_f32 v[64:65], v[40:41], v[92:93], v[64:65]
	v_rcp_f32_e32 v68, v68
	v_rcp_f32_e32 v69, v69
	v_mov_b64_e32 v[90:91], s[70:71]
	v_pk_fma_f32 v[10:11], v[10:11], v[78:79], v[82:83]
	v_pk_fma_f32 v[12:13], v[12:13], v[80:81], v[84:85]
	v_pk_mul_f32 v[28:29], v[28:29], v[68:69]
	s_nop 0
	v_pk_mul_f32 v[28:29], v[64:65], v[28:29]
	v_cvt_pk_bf16_f32 v64, v44, v45
	v_pk_fma_f32 v[44:45], v[18:19], v[78:79], v[82:83]
	v_cvt_pk_bf16_f32 v65, v28, v29
	v_mad_i64_i32 v[28:29], s[8:9], v0, s77, v[90:91]
	v_lshl_add_u64 v[28:29], v[28:29], 0, v[154:155]
	global_store_dwordx4 v[28:29], v[62:65], off
	v_pk_fma_f32 v[44:45], v[30:31], v[74:75], v[44:45]
	v_pk_fma_f32 v[28:29], v[20:21], v[80:81], v[84:85]
	v_pk_fma_f32 v[64:65], v[22:23], v[54:55], v[70:71]
	v_pk_fma_f32 v[44:45], v[46:47], v[86:87], v[44:45]
	v_pk_fma_f32 v[64:65], v[34:35], v[50:51], v[64:65]
	v_pk_fma_f32 v[28:29], v[32:33], v[76:77], v[28:29]
	v_pk_fma_f32 v[58:59], v[38:39], v[58:59], v[64:65]
	v_pk_mul_f32 v[64:65], v[44:45], s[88:89] op_sel_hi:[1,0]
	v_pk_fma_f32 v[62:63], v[24:25], v[56:57], v[72:73]
	v_exp_f32_e32 v64, v64
	v_exp_f32_e32 v65, v65
	v_pk_fma_f32 v[62:63], v[36:37], v[52:53], v[62:63]
	v_pk_fma_f32 v[28:29], v[48:49], v[88:89], v[28:29]
	v_add_u32_e32 v0, 0x81, v194
	v_pk_add_f32 v[64:65], v[64:65], 1.0 op_sel_hi:[1,0]
	s_nop 0
	v_rcp_f32_e32 v64, v64
	v_rcp_f32_e32 v65, v65
	s_nop 0
	v_pk_mul_f32 v[44:45], v[44:45], v[64:65]
	s_nop 0
	v_pk_mul_f32 v[44:45], v[58:59], v[44:45]
	v_pk_fma_f32 v[58:59], v[40:41], v[60:61], v[62:63]
	v_pk_mul_f32 v[60:61], v[28:29], s[88:89] op_sel_hi:[1,0]
	v_cvt_pk_bf16_f32 v68, v44, v45
	v_pk_fma_f32 v[44:45], v[2:3], v[78:79], v[82:83]
	v_exp_f32_e32 v60, v60
	v_exp_f32_e32 v61, v61
	v_pk_fma_f32 v[44:45], v[18:19], v[74:75], v[44:45]
	v_pk_fma_f32 v[2:3], v[2:3], v[74:75], v[10:11]
	v_pk_fma_f32 v[30:31], v[30:31], v[46:47], v[44:45]
	v_pk_add_f32 v[60:61], v[60:61], 1.0 op_sel_hi:[1,0]
	v_pk_fma_f32 v[2:3], v[18:19], v[46:47], v[2:3]
	v_rcp_f32_e32 v60, v60
	v_rcp_f32_e32 v61, v61
	v_pk_fma_f32 v[10:11], v[16:17], v[56:57], v[72:73]
	v_pk_fma_f32 v[44:45], v[6:7], v[54:55], v[70:71]
	v_pk_mul_f32 v[28:29], v[28:29], v[60:61]
	s_nop 0
	v_pk_mul_f32 v[28:29], v[58:59], v[28:29]
	v_pk_fma_f32 v[44:45], v[22:23], v[50:51], v[44:45]
	v_cvt_pk_bf16_f32 v69, v28, v29
	v_mad_i64_i32 v[28:29], s[8:9], v0, s77, v[90:91]
	v_lshl_add_u64 v[28:29], v[28:29], 0, v[154:155]
	global_store_dwordx4 v[28:29], v[66:69], off
	v_pk_fma_f32 v[28:29], v[4:5], v[80:81], v[84:85]
	v_pk_fma_f32 v[34:35], v[34:35], v[38:39], v[44:45]
	v_pk_fma_f32 v[28:29], v[20:21], v[76:77], v[28:29]
	v_pk_fma_f32 v[4:5], v[4:5], v[76:77], v[12:13]
	v_pk_fma_f32 v[28:29], v[32:33], v[48:49], v[28:29]
	v_pk_fma_f32 v[32:33], v[8:9], v[56:57], v[72:73]
	v_pk_fma_f32 v[8:9], v[8:9], v[52:53], v[10:11]
	v_pk_fma_f32 v[32:33], v[24:25], v[52:53], v[32:33]
	v_pk_mul_f32 v[10:11], v[2:3], s[88:89] op_sel_hi:[1,0]
	v_pk_fma_f32 v[32:33], v[36:37], v[40:41], v[32:33]
	v_pk_mul_f32 v[36:37], v[30:31], s[88:89] op_sel_hi:[1,0]
	v_exp_f32_e32 v10, v10
	v_exp_f32_e32 v36, v36
	v_exp_f32_e32 v37, v37
	v_exp_f32_e32 v11, v11
	v_pk_fma_f32 v[12:13], v[14:15], v[54:55], v[70:71]
	v_pk_fma_f32 v[4:5], v[20:21], v[48:49], v[4:5]
	v_pk_add_f32 v[36:37], v[36:37], 1.0 op_sel_hi:[1,0]
	v_pk_add_f32 v[10:11], v[10:11], 1.0 op_sel_hi:[1,0]
	v_rcp_f32_e32 v36, v36
	v_rcp_f32_e32 v37, v37
	v_rcp_f32_e32 v10, v10
	v_rcp_f32_e32 v11, v11
	v_pk_fma_f32 v[6:7], v[6:7], v[50:51], v[12:13]
	v_pk_mul_f32 v[30:31], v[30:31], v[36:37]
	v_pk_fma_f32 v[6:7], v[22:23], v[38:39], v[6:7]
	v_pk_mul_f32 v[30:31], v[34:35], v[30:31]
	v_pk_mul_f32 v[34:35], v[28:29], s[88:89] op_sel_hi:[1,0]
	v_pk_mul_f32 v[2:3], v[2:3], v[10:11]
	v_exp_f32_e32 v34, v34
	v_exp_f32_e32 v35, v35
	v_pk_mul_f32 v[2:3], v[6:7], v[2:3]
	v_pk_mul_f32 v[6:7], v[4:5], s[88:89] op_sel_hi:[1,0]
	v_add_u32_e32 v0, 0x82, v194
	v_pk_add_f32 v[34:35], v[34:35], 1.0 op_sel_hi:[1,0]
	v_exp_f32_e32 v6, v6
	v_rcp_f32_e32 v34, v34
	v_rcp_f32_e32 v35, v35
	v_exp_f32_e32 v7, v7
	v_cvt_pk_bf16_f32 v44, v30, v31
	v_pk_fma_f32 v[8:9], v[24:25], v[40:41], v[8:9]
	v_pk_mul_f32 v[28:29], v[28:29], v[34:35]
	v_pk_add_f32 v[6:7], v[6:7], 1.0 op_sel_hi:[1,0]
	v_pk_mul_f32 v[28:29], v[32:33], v[28:29]
	v_rcp_f32_e32 v6, v6
	v_rcp_f32_e32 v7, v7
	v_cvt_pk_bf16_f32 v45, v28, v29
	v_mad_i64_i32 v[28:29], s[8:9], v0, s77, v[90:91]
	v_lshl_add_u64 v[28:29], v[28:29], 0, v[154:155]
	v_add_u32_e32 v0, 0x83, v194
	global_store_dwordx4 v[28:29], v[42:45], off
	v_cvt_pk_bf16_f32 v28, v2, v3
	v_mad_i64_i32 v[2:3], s[8:9], v0, s77, v[90:91]
	v_pk_mul_f32 v[4:5], v[4:5], v[6:7]
	v_lshl_add_u64 v[2:3], v[2:3], 0, v[154:155]
	v_pk_mul_f32 v[4:5], v[8:9], v[4:5]
	s_nop 0
	v_cvt_pk_bf16_f32 v29, v4, v5
	global_store_dwordx4 v[2:3], v[26:29], off
	s_andn2_b64 vcc, exec, s[42:43]
	s_cbranch_vccnz .LBB0_747
; #define LAS __attribute__((address_space(3)))
;     __device__ __forceinline__ void operator()(f32x4 (&acc)[2][2][4][2], const Unit& u, int wr, int wc, int fr, int fq, int next_pn) const {
;     ...
;         if (next_pn >= 0) { *(LAS f32x2v*)(WL0 + (1 - bcur) * 1024 + wl_idx) = wn2; }
;         if (4 * wr + wc == 0 && fq == 0 && fr == 0) { wtag[bcur] = u.pn; wtag[1 - bcur] = next_pn; }
	s_and_b64 s[8:9], s[6:7], exec
	s_cselect_b32 s8, 0, 0x1000
	s_add_i32 s8, s8, 0
	v_lshl_add_u32 v0, v208, 2, s8
	v_add_u32_e32 v0, 0x22100, v0
	s_waitcnt vmcnt(8)
	ds_write_b64 v0, v[192:193]
